# v21 plus MLA back-edge rotation plus 64-byte aligned GEMM K-loop heads and MLA loop entry
# speedup vs baseline: 1.0049x; 1.0049x over previous
;     ...
; #pragma unroll
;         for (int a = 0; a < 2; ++a)
; #pragma unroll
;             for (int b = 0; b < 2; ++b)
; #pragma unroll
;                 for (int m = 0; m < 4; ++m)
; #pragma unroll
;                     for (int n = 0; n < 2; ++n) acc[a][b][m][n] = (f32x4){0.f, 0.f, 0.f, 0.f};
;         cur = nxt; cA = nA; cB = nB; nt = cur.nt; ++ui;
.LBB0_406:
	s_ashr_i32 s25, s24, 31
	s_lshl_b64 s[26:27], s[24:25], 20
	s_add_u32 s26, s80, s26
	s_addc_u32 s27, s81, s27
	s_and_b64 s[38:39], s[6:7], exec
	s_cselect_b32 s9, s27, s31
	s_cselect_b32 s25, s26, s30
	s_ashr_i32 s93, s92, 31
	s_lshl_b64 s[38:39], s[92:93], 20
	s_add_u32 s38, s22, s38
	s_addc_u32 s39, s23, s39
	s_and_b64 s[42:43], s[6:7], exec
	s_cselect_b32 s33, s39, s29
	s_cselect_b32 s40, s38, s28
	s_add_u32 s30, s30, 0x80080
	s_addc_u32 s31, s31, 0
	s_add_u32 s48, s28, 0x100
	v_mov_b32_e32 v2, 0
	s_addc_u32 s50, s29, 0
	s_mov_b32 s93, -2
	v_mov_b32_e32 v3, v2
	v_mov_b32_e32 v4, v2
	v_mov_b32_e32 v5, v2
	v_mov_b32_e32 v6, v2
	v_mov_b32_e32 v7, v2
	v_mov_b32_e32 v8, v2
	v_mov_b32_e32 v9, v2
	v_mov_b32_e32 v18, v2
	v_mov_b32_e32 v19, v2
	v_mov_b32_e32 v20, v2
	v_mov_b32_e32 v21, v2
	v_mov_b32_e32 v22, v2
	v_mov_b32_e32 v23, v2
	v_mov_b32_e32 v24, v2
	v_mov_b32_e32 v25, v2
	v_mov_b32_e32 v40, v2
	v_mov_b32_e32 v41, v2
	v_mov_b32_e32 v42, v2
	v_mov_b32_e32 v43, v2
	v_mov_b32_e32 v44, v2
	v_mov_b32_e32 v45, v2
	v_mov_b32_e32 v46, v2
	v_mov_b32_e32 v47, v2
	v_mov_b32_e32 v56, v2
	v_mov_b32_e32 v57, v2
	v_mov_b32_e32 v58, v2
	v_mov_b32_e32 v59, v2
	v_mov_b32_e32 v60, v2
	v_mov_b32_e32 v61, v2
	v_mov_b32_e32 v62, v2
	v_mov_b32_e32 v63, v2
	v_mov_b32_e32 v10, v2
	v_mov_b32_e32 v11, v2
	v_mov_b32_e32 v12, v2
	v_mov_b32_e32 v13, v2
	v_mov_b32_e32 v14, v2
	v_mov_b32_e32 v15, v2
	v_mov_b32_e32 v16, v2
	v_mov_b32_e32 v17, v2
	v_mov_b32_e32 v26, v2
	v_mov_b32_e32 v27, v2
	v_mov_b32_e32 v28, v2
	v_mov_b32_e32 v29, v2
	v_mov_b32_e32 v36, v2
	v_mov_b32_e32 v37, v2
	v_mov_b32_e32 v38, v2
	v_mov_b32_e32 v39, v2
	v_mov_b32_e32 v48, v2
	v_mov_b32_e32 v49, v2
	v_mov_b32_e32 v50, v2
	v_mov_b32_e32 v51, v2
	v_mov_b32_e32 v52, v2
	v_mov_b32_e32 v53, v2
	v_mov_b32_e32 v54, v2
	v_mov_b32_e32 v55, v2
	v_mov_b32_e32 v64, v2
	v_mov_b32_e32 v65, v2
	v_mov_b32_e32 v66, v2
	v_mov_b32_e32 v67, v2
	v_mov_b32_e32 v68, v2
	v_mov_b32_e32 v69, v2
	v_mov_b32_e32 v70, v2
	v_mov_b32_e32 v71, v2
	v_mov_b32_e32 v72, v2
	v_mov_b32_e32 v73, v2
	v_mov_b32_e32 v74, v2
	v_mov_b32_e32 v75, v2
	v_mov_b32_e32 v76, v2
	v_mov_b32_e32 v77, v2
	v_mov_b32_e32 v78, v2
	v_mov_b32_e32 v79, v2
	v_mov_b32_e32 v88, v2
	v_mov_b32_e32 v89, v2
	v_mov_b32_e32 v90, v2
	v_mov_b32_e32 v91, v2
	v_mov_b32_e32 v92, v2
	v_mov_b32_e32 v93, v2
	v_mov_b32_e32 v94, v2
	v_mov_b32_e32 v95, v2
	v_mov_b32_e32 v104, v2
	v_mov_b32_e32 v105, v2
	v_mov_b32_e32 v106, v2
	v_mov_b32_e32 v107, v2
	v_mov_b32_e32 v108, v2
	v_mov_b32_e32 v109, v2
	v_mov_b32_e32 v110, v2
	v_mov_b32_e32 v111, v2
	v_mov_b32_e32 v120, v2
	v_mov_b32_e32 v121, v2
	v_mov_b32_e32 v122, v2
	v_mov_b32_e32 v123, v2
	v_mov_b32_e32 v124, v2
	v_mov_b32_e32 v125, v2
	v_mov_b32_e32 v126, v2
	v_mov_b32_e32 v127, v2
	v_mov_b32_e32 v80, v2
	v_mov_b32_e32 v81, v2
	v_mov_b32_e32 v82, v2
	v_mov_b32_e32 v83, v2
	v_mov_b32_e32 v84, v2
	v_mov_b32_e32 v85, v2
	v_mov_b32_e32 v86, v2
	v_mov_b32_e32 v87, v2
	v_mov_b32_e32 v96, v2
	v_mov_b32_e32 v97, v2
	v_mov_b32_e32 v98, v2
	v_mov_b32_e32 v99, v2
	v_mov_b32_e32 v100, v2
	v_mov_b32_e32 v101, v2
	v_mov_b32_e32 v102, v2
	v_mov_b32_e32 v103, v2
	v_mov_b32_e32 v112, v2
	v_mov_b32_e32 v113, v2
	v_mov_b32_e32 v114, v2
	v_mov_b32_e32 v115, v2
	v_mov_b32_e32 v116, v2
	v_mov_b32_e32 v117, v2
	v_mov_b32_e32 v118, v2
	v_mov_b32_e32 v119, v2
	v_mov_b32_e32 v128, v2
	v_mov_b32_e32 v129, v2
	v_mov_b32_e32 v130, v2
	v_mov_b32_e32 v131, v2
	v_mov_b32_e32 v132, v2
	v_mov_b32_e32 v133, v2
	v_mov_b32_e32 v134, v2
	v_mov_b32_e32 v135, v2
	.p2align 6

;     ...
; #pragma unroll
;         for (int a = 0; a < 2; ++a)
; #pragma unroll
;             for (int b = 0; b < 2; ++b)
; #pragma unroll
;                 for (int m = 0; m < 4; ++m)
; #pragma unroll
;                     for (int n = 0; n < 2; ++n) acc[a][b][m][n] = (f32x4){0.f, 0.f, 0.f, 0.f};
;         cur = nxt; cA = nA; cB = nB; nt = cur.nt; ++ui;
.LBB0_747:
	s_ashr_i32 s11, s10, 31
	s_lshl_b64 s[14:15], s[10:11], 18
	s_add_u32 s14, s22, s14
	s_addc_u32 s15, s23, s15
	s_and_b64 s[4:5], s[4:5], exec
	s_cselect_b32 s11, s15, s25
	s_cselect_b32 s33, s14, s24
	s_add_u32 s48, s24, 0x100
	v_mov_b32_e32 v2, 0
	s_addc_u32 s74, s25, 0
	s_mov_b32 s78, -2
	v_mov_b32_e32 v3, v2
	v_mov_b32_e32 v4, v2
	v_mov_b32_e32 v5, v2
	v_mov_b32_e32 v6, v2
	v_mov_b32_e32 v7, v2
	v_mov_b32_e32 v8, v2
	v_mov_b32_e32 v9, v2
	v_mov_b32_e32 v18, v2
	v_mov_b32_e32 v19, v2
	v_mov_b32_e32 v20, v2
	v_mov_b32_e32 v21, v2
	v_mov_b32_e32 v22, v2
	v_mov_b32_e32 v23, v2
	v_mov_b32_e32 v24, v2
	v_mov_b32_e32 v25, v2
	v_mov_b32_e32 v38, v2
	v_mov_b32_e32 v39, v2
	v_mov_b32_e32 v40, v2
	v_mov_b32_e32 v41, v2
	v_mov_b32_e32 v42, v2
	v_mov_b32_e32 v43, v2
	v_mov_b32_e32 v44, v2
	v_mov_b32_e32 v45, v2
	v_mov_b32_e32 v54, v2
	v_mov_b32_e32 v55, v2
	v_mov_b32_e32 v56, v2
	v_mov_b32_e32 v57, v2
	v_mov_b32_e32 v58, v2
	v_mov_b32_e32 v59, v2
	v_mov_b32_e32 v60, v2
	v_mov_b32_e32 v61, v2
	v_mov_b32_e32 v10, v2
	v_mov_b32_e32 v11, v2
	v_mov_b32_e32 v12, v2
	v_mov_b32_e32 v13, v2
	v_mov_b32_e32 v14, v2
	v_mov_b32_e32 v15, v2
	v_mov_b32_e32 v16, v2
	v_mov_b32_e32 v17, v2
	v_mov_b32_e32 v26, v2
	v_mov_b32_e32 v27, v2
	v_mov_b32_e32 v28, v2
	v_mov_b32_e32 v29, v2
	v_mov_b32_e32 v34, v2
	v_mov_b32_e32 v35, v2
	v_mov_b32_e32 v36, v2
	v_mov_b32_e32 v37, v2
	v_mov_b32_e32 v46, v2
	v_mov_b32_e32 v47, v2
	v_mov_b32_e32 v48, v2
	v_mov_b32_e32 v49, v2
	v_mov_b32_e32 v50, v2
	v_mov_b32_e32 v51, v2
	v_mov_b32_e32 v52, v2
	v_mov_b32_e32 v53, v2
	v_mov_b32_e32 v62, v2
	v_mov_b32_e32 v63, v2
	v_mov_b32_e32 v64, v2
	v_mov_b32_e32 v65, v2
	v_mov_b32_e32 v66, v2
	v_mov_b32_e32 v67, v2
	v_mov_b32_e32 v68, v2
	v_mov_b32_e32 v69, v2
	v_mov_b32_e32 v70, v2
	v_mov_b32_e32 v71, v2
	v_mov_b32_e32 v72, v2
	v_mov_b32_e32 v73, v2
	v_mov_b32_e32 v74, v2
	v_mov_b32_e32 v75, v2
	v_mov_b32_e32 v76, v2
	v_mov_b32_e32 v77, v2
	v_mov_b32_e32 v86, v2
	v_mov_b32_e32 v87, v2
	v_mov_b32_e32 v88, v2
	v_mov_b32_e32 v89, v2
	v_mov_b32_e32 v90, v2
	v_mov_b32_e32 v91, v2
	v_mov_b32_e32 v92, v2
	v_mov_b32_e32 v93, v2
	v_mov_b32_e32 v102, v2
	v_mov_b32_e32 v103, v2
	v_mov_b32_e32 v104, v2
	v_mov_b32_e32 v105, v2
	v_mov_b32_e32 v106, v2
	v_mov_b32_e32 v107, v2
	v_mov_b32_e32 v108, v2
	v_mov_b32_e32 v109, v2
	v_mov_b32_e32 v118, v2
	v_mov_b32_e32 v119, v2
	v_mov_b32_e32 v120, v2
	v_mov_b32_e32 v121, v2
	v_mov_b32_e32 v122, v2
	v_mov_b32_e32 v123, v2
	v_mov_b32_e32 v124, v2
	v_mov_b32_e32 v125, v2
	v_mov_b32_e32 v78, v2
	v_mov_b32_e32 v79, v2
	v_mov_b32_e32 v80, v2
	v_mov_b32_e32 v81, v2
	v_mov_b32_e32 v82, v2
	v_mov_b32_e32 v83, v2
	v_mov_b32_e32 v84, v2
	v_mov_b32_e32 v85, v2
	v_mov_b32_e32 v94, v2
	v_mov_b32_e32 v95, v2
	v_mov_b32_e32 v96, v2
	v_mov_b32_e32 v97, v2
	v_mov_b32_e32 v98, v2
	v_mov_b32_e32 v99, v2
	v_mov_b32_e32 v100, v2
	v_mov_b32_e32 v101, v2
	v_mov_b32_e32 v110, v2
	v_mov_b32_e32 v111, v2
	v_mov_b32_e32 v112, v2
	v_mov_b32_e32 v113, v2
	v_mov_b32_e32 v114, v2
	v_mov_b32_e32 v115, v2
	v_mov_b32_e32 v116, v2
	v_mov_b32_e32 v117, v2
	v_mov_b32_e32 v126, v2
	v_mov_b32_e32 v127, v2
	v_mov_b32_e32 v128, v2
	v_mov_b32_e32 v129, v2
	v_mov_b32_e32 v130, v2
	v_mov_b32_e32 v131, v2
	v_mov_b32_e32 v132, v2
	v_mov_b32_e32 v133, v2
	.p2align 6

;     ...
; #pragma unroll
;         for (int a = 0; a < 2; ++a)
; #pragma unroll
;             for (int b = 0; b < 2; ++b)
; #pragma unroll
;                 for (int m = 0; m < 4; ++m)
; #pragma unroll
;                     for (int n = 0; n < 2; ++n) acc[a][b][m][n] = (f32x4){0.f, 0.f, 0.f, 0.f};
;         cur = nxt; cA = nA; cB = nB; nt = cur.nt; ++ui;
.LBB0_765:
	s_ashr_i32 s13, s12, 31
	s_lshl_b64 s[6:7], s[12:13], 17
	v_readlane_b32 s16, v255, 5
	v_readlane_b32 s17, v255, 6
	s_add_u32 s16, s16, s6
	s_addc_u32 s17, s17, s7
	s_and_b64 s[4:5], s[4:5], exec
	v_mov_b32_e32 v2, 0
	s_cselect_b32 s13, s17, s23
	s_cselect_b32 s33, s16, s22
	s_mov_b32 s28, 0
	s_mov_b64 s[4:5], -1
	s_mov_b64 s[26:27], 0
	v_mov_b32_e32 v3, v2
	v_mov_b32_e32 v4, v2
	v_mov_b32_e32 v5, v2
	v_mov_b32_e32 v6, v2
	v_mov_b32_e32 v7, v2
	v_mov_b32_e32 v8, v2
	v_mov_b32_e32 v9, v2
	v_mov_b32_e32 v18, v2
	v_mov_b32_e32 v19, v2
	v_mov_b32_e32 v20, v2
	v_mov_b32_e32 v21, v2
	v_mov_b32_e32 v22, v2
	v_mov_b32_e32 v23, v2
	v_mov_b32_e32 v24, v2
	v_mov_b32_e32 v25, v2
	v_mov_b32_e32 v38, v2
	v_mov_b32_e32 v39, v2
	v_mov_b32_e32 v40, v2
	v_mov_b32_e32 v41, v2
	v_mov_b32_e32 v42, v2
	v_mov_b32_e32 v43, v2
	v_mov_b32_e32 v44, v2
	v_mov_b32_e32 v45, v2
	v_mov_b32_e32 v54, v2
	v_mov_b32_e32 v55, v2
	v_mov_b32_e32 v56, v2
	v_mov_b32_e32 v57, v2
	v_mov_b32_e32 v58, v2
	v_mov_b32_e32 v59, v2
	v_mov_b32_e32 v60, v2
	v_mov_b32_e32 v61, v2
	v_mov_b32_e32 v10, v2
	v_mov_b32_e32 v11, v2
	v_mov_b32_e32 v12, v2
	v_mov_b32_e32 v13, v2
	v_mov_b32_e32 v14, v2
	v_mov_b32_e32 v15, v2
	v_mov_b32_e32 v16, v2
	v_mov_b32_e32 v17, v2
	v_mov_b32_e32 v26, v2
	v_mov_b32_e32 v27, v2
	v_mov_b32_e32 v28, v2
	v_mov_b32_e32 v29, v2
	v_mov_b32_e32 v34, v2
	v_mov_b32_e32 v35, v2
	v_mov_b32_e32 v36, v2
	v_mov_b32_e32 v37, v2
	v_mov_b32_e32 v46, v2
	v_mov_b32_e32 v47, v2
	v_mov_b32_e32 v48, v2
	v_mov_b32_e32 v49, v2
	v_mov_b32_e32 v50, v2
	v_mov_b32_e32 v51, v2
	v_mov_b32_e32 v52, v2
	v_mov_b32_e32 v53, v2
	v_mov_b32_e32 v62, v2
	v_mov_b32_e32 v63, v2
	v_mov_b32_e32 v64, v2
	v_mov_b32_e32 v65, v2
	v_mov_b32_e32 v66, v2
	v_mov_b32_e32 v67, v2
	v_mov_b32_e32 v68, v2
	v_mov_b32_e32 v69, v2
	v_mov_b32_e32 v70, v2
	v_mov_b32_e32 v71, v2
	v_mov_b32_e32 v72, v2
	v_mov_b32_e32 v73, v2
	v_mov_b32_e32 v74, v2
	v_mov_b32_e32 v75, v2
	v_mov_b32_e32 v76, v2
	v_mov_b32_e32 v77, v2
	v_mov_b32_e32 v86, v2
	v_mov_b32_e32 v87, v2
	v_mov_b32_e32 v88, v2
	v_mov_b32_e32 v89, v2
	v_mov_b32_e32 v90, v2
	v_mov_b32_e32 v91, v2
	v_mov_b32_e32 v92, v2
	v_mov_b32_e32 v93, v2
	v_mov_b32_e32 v102, v2
	v_mov_b32_e32 v103, v2
	v_mov_b32_e32 v104, v2
	v_mov_b32_e32 v105, v2
	v_mov_b32_e32 v106, v2
	v_mov_b32_e32 v107, v2
	v_mov_b32_e32 v108, v2
	v_mov_b32_e32 v109, v2
	v_mov_b32_e32 v118, v2
	v_mov_b32_e32 v119, v2
	v_mov_b32_e32 v120, v2
	v_mov_b32_e32 v121, v2
	v_mov_b32_e32 v122, v2
	v_mov_b32_e32 v123, v2
	v_mov_b32_e32 v124, v2
	v_mov_b32_e32 v125, v2
	v_mov_b32_e32 v78, v2
	v_mov_b32_e32 v79, v2
	v_mov_b32_e32 v80, v2
	v_mov_b32_e32 v81, v2
	v_mov_b32_e32 v82, v2
	v_mov_b32_e32 v83, v2
	v_mov_b32_e32 v84, v2
	v_mov_b32_e32 v85, v2
	v_mov_b32_e32 v94, v2
	v_mov_b32_e32 v95, v2
	v_mov_b32_e32 v96, v2
	v_mov_b32_e32 v97, v2
	v_mov_b32_e32 v98, v2
	v_mov_b32_e32 v99, v2
	v_mov_b32_e32 v100, v2
	v_mov_b32_e32 v101, v2
	v_mov_b32_e32 v110, v2
	v_mov_b32_e32 v111, v2
	v_mov_b32_e32 v112, v2
	v_mov_b32_e32 v113, v2
	v_mov_b32_e32 v114, v2
	v_mov_b32_e32 v115, v2
	v_mov_b32_e32 v116, v2
	v_mov_b32_e32 v117, v2
	v_mov_b32_e32 v126, v2
	v_mov_b32_e32 v127, v2
	v_mov_b32_e32 v128, v2
	v_mov_b32_e32 v129, v2
	v_mov_b32_e32 v130, v2
	v_mov_b32_e32 v131, v2
	v_mov_b32_e32 v132, v2
	v_mov_b32_e32 v133, v2
	.p2align 6

; #define LAS __attribute__((address_space(3)))
; __device__ __forceinline__ void mla_unit(const bf16* QM, const bf16* KVM, const bf16* KR, bf16* Y, int b, int h, int qrow0, int ntiles, bool latent, LAS unsigned char* L, int tid_in) {
;     ...
;     for (int t = 0; t < ntiles; ++t) {
;         LAS const unsigned char* Kt = L + bcur * MLA_BUF;
;         f32x16 p[2];
;         __builtin_amdgcn_sched_barrier(0);
;         attn_scores<192, MLA_KSB>(Kt, qf, p, r32, hi);
.LBB0_970:
	s_mul_i32 s12, s11, 0xb400
	s_add_i32 s12, s12, 0
	v_add3_u32 v32, s12, v207, v30
	.p2align 6

;     ...
; #pragma unroll
;         for (int a = 0; a < 2; ++a)
; #pragma unroll
;             for (int b = 0; b < 2; ++b)
; #pragma unroll
;                 for (int m = 0; m < 4; ++m)
; #pragma unroll
;                     for (int n = 0; n < 2; ++n) acc[a][b][m][n] = (f32x4){0.f, 0.f, 0.f, 0.f};
;         cur = nxt; cA = nA; cB = nB; nt = cur.nt; ++ui;
.LBB0_1063:
	s_add_u32 s9, s30, 0x100
	v_mov_b32_e32 v2, 0
	s_addc_u32 s17, s31, 0
	s_mov_b32 s19, 2
	v_mov_b32_e32 v3, v2
	v_mov_b32_e32 v4, v2
	v_mov_b32_e32 v5, v2
	v_mov_b32_e32 v6, v2
	v_mov_b32_e32 v7, v2
	v_mov_b32_e32 v8, v2
	v_mov_b32_e32 v9, v2
	v_mov_b32_e32 v18, v2
	v_mov_b32_e32 v19, v2
	v_mov_b32_e32 v20, v2
	v_mov_b32_e32 v21, v2
	v_mov_b32_e32 v22, v2
	v_mov_b32_e32 v23, v2
	v_mov_b32_e32 v24, v2
	v_mov_b32_e32 v25, v2
	v_mov_b32_e32 v40, v2
	v_mov_b32_e32 v41, v2
	v_mov_b32_e32 v42, v2
	v_mov_b32_e32 v43, v2
	v_mov_b32_e32 v44, v2
	v_mov_b32_e32 v45, v2
	v_mov_b32_e32 v46, v2
	v_mov_b32_e32 v47, v2
	v_mov_b32_e32 v56, v2
	v_mov_b32_e32 v57, v2
	v_mov_b32_e32 v58, v2
	v_mov_b32_e32 v59, v2
	v_mov_b32_e32 v60, v2
	v_mov_b32_e32 v61, v2
	v_mov_b32_e32 v62, v2
	v_mov_b32_e32 v63, v2
	v_mov_b32_e32 v10, v2
	v_mov_b32_e32 v11, v2
	v_mov_b32_e32 v12, v2
	v_mov_b32_e32 v13, v2
	v_mov_b32_e32 v14, v2
	v_mov_b32_e32 v15, v2
	v_mov_b32_e32 v16, v2
	v_mov_b32_e32 v17, v2
	v_mov_b32_e32 v26, v2
	v_mov_b32_e32 v27, v2
	v_mov_b32_e32 v28, v2
	v_mov_b32_e32 v29, v2
	v_mov_b32_e32 v36, v2
	v_mov_b32_e32 v37, v2
	v_mov_b32_e32 v38, v2
	v_mov_b32_e32 v39, v2
	v_mov_b32_e32 v48, v2
	v_mov_b32_e32 v49, v2
	v_mov_b32_e32 v50, v2
	v_mov_b32_e32 v51, v2
	v_mov_b32_e32 v52, v2
	v_mov_b32_e32 v53, v2
	v_mov_b32_e32 v54, v2
	v_mov_b32_e32 v55, v2
	v_mov_b32_e32 v64, v2
	v_mov_b32_e32 v65, v2
	v_mov_b32_e32 v66, v2
	v_mov_b32_e32 v67, v2
	v_mov_b32_e32 v68, v2
	v_mov_b32_e32 v69, v2
	v_mov_b32_e32 v70, v2
	v_mov_b32_e32 v71, v2
	v_mov_b32_e32 v92, v2
	v_mov_b32_e32 v93, v2
	v_mov_b32_e32 v94, v2
	v_mov_b32_e32 v95, v2
	v_mov_b32_e32 v96, v2
	v_mov_b32_e32 v97, v2
	v_mov_b32_e32 v98, v2
	v_mov_b32_e32 v99, v2
	v_mov_b32_e32 v108, v2
	v_mov_b32_e32 v109, v2
	v_mov_b32_e32 v110, v2
	v_mov_b32_e32 v111, v2
	v_mov_b32_e32 v112, v2
	v_mov_b32_e32 v113, v2
	v_mov_b32_e32 v114, v2
	v_mov_b32_e32 v115, v2
	v_mov_b32_e32 v124, v2
	v_mov_b32_e32 v125, v2
	v_mov_b32_e32 v126, v2
	v_mov_b32_e32 v127, v2
	v_mov_b32_e32 v128, v2
	v_mov_b32_e32 v129, v2
	v_mov_b32_e32 v130, v2
	v_mov_b32_e32 v131, v2
	v_mov_b32_e32 v140, v2
	v_mov_b32_e32 v141, v2
	v_mov_b32_e32 v142, v2
	v_mov_b32_e32 v143, v2
	v_mov_b32_e32 v144, v2
	v_mov_b32_e32 v145, v2
	v_mov_b32_e32 v146, v2
	v_mov_b32_e32 v147, v2
	v_mov_b32_e32 v100, v2
	v_mov_b32_e32 v101, v2
	v_mov_b32_e32 v102, v2
	v_mov_b32_e32 v103, v2
	v_mov_b32_e32 v104, v2
	v_mov_b32_e32 v105, v2
	v_mov_b32_e32 v106, v2
	v_mov_b32_e32 v107, v2
	v_mov_b32_e32 v116, v2
	v_mov_b32_e32 v117, v2
	v_mov_b32_e32 v118, v2
	v_mov_b32_e32 v119, v2
	v_mov_b32_e32 v120, v2
	v_mov_b32_e32 v121, v2
	v_mov_b32_e32 v122, v2
	v_mov_b32_e32 v123, v2
	v_mov_b32_e32 v132, v2
	v_mov_b32_e32 v133, v2
	v_mov_b32_e32 v134, v2
	v_mov_b32_e32 v135, v2
	v_mov_b32_e32 v136, v2
	v_mov_b32_e32 v137, v2
	v_mov_b32_e32 v138, v2
	v_mov_b32_e32 v139, v2
	v_mov_b32_e32 v148, v2
	v_mov_b32_e32 v149, v2
	v_mov_b32_e32 v150, v2
	v_mov_b32_e32 v151, v2
	v_mov_b32_e32 v84, v2
	v_mov_b32_e32 v85, v2
	v_mov_b32_e32 v86, v2
	v_mov_b32_e32 v87, v2
	.p2align 6

;     ...
; #pragma unroll
;         for (int a = 0; a < 2; ++a)
; #pragma unroll
;             for (int b = 0; b < 2; ++b)
; #pragma unroll
;                 for (int m = 0; m < 4; ++m)
; #pragma unroll
;                     for (int n = 0; n < 2; ++n) acc[a][b][m][n] = (f32x4){0.f, 0.f, 0.f, 0.f};
;         cur = nxt; cA = nA; cB = nB; nt = cur.nt; ++ui;
.LBB0_1331:
	s_ashr_i32 s11, s10, 31
	s_lshl_b64 s[12:13], s[10:11], 20
	s_add_u32 s12, s80, s12
	s_addc_u32 s13, s81, s13
	s_and_b64 s[14:15], s[16:17], exec
	s_cselect_b32 s11, s13, s25
	s_cselect_b32 s48, s12, s24
	s_ashr_i32 s9, s8, 31
	s_lshl_b64 s[14:15], s[8:9], 20
	v_readlane_b32 s28, v254, 55
	v_readlane_b32 s29, v254, 56
	s_add_u32 s14, s28, s14
	s_addc_u32 s15, s29, s15
	s_and_b64 s[28:29], s[16:17], exec
	s_cselect_b32 s9, s15, s27
	s_cselect_b32 s33, s14, s26
	s_add_u32 s24, s24, 0x80080
	s_addc_u32 s25, s25, 0
	s_add_u32 s74, s26, 0x100
	v_mov_b32_e32 v2, 0
	s_addc_u32 s78, s27, 0
	s_mov_b32 s79, -2
	v_mov_b32_e32 v3, v2
	v_mov_b32_e32 v4, v2
	v_mov_b32_e32 v5, v2
	v_mov_b32_e32 v6, v2
	v_mov_b32_e32 v7, v2
	v_mov_b32_e32 v8, v2
	v_mov_b32_e32 v9, v2
	v_mov_b32_e32 v18, v2
	v_mov_b32_e32 v19, v2
	v_mov_b32_e32 v20, v2
	v_mov_b32_e32 v21, v2
	v_mov_b32_e32 v22, v2
	v_mov_b32_e32 v23, v2
	v_mov_b32_e32 v24, v2
	v_mov_b32_e32 v25, v2
	v_mov_b32_e32 v38, v2
	v_mov_b32_e32 v39, v2
	v_mov_b32_e32 v40, v2
	v_mov_b32_e32 v41, v2
	v_mov_b32_e32 v42, v2
	v_mov_b32_e32 v43, v2
	v_mov_b32_e32 v44, v2
	v_mov_b32_e32 v45, v2
	v_mov_b32_e32 v54, v2
	v_mov_b32_e32 v55, v2
	v_mov_b32_e32 v56, v2
	v_mov_b32_e32 v57, v2
	v_mov_b32_e32 v58, v2
	v_mov_b32_e32 v59, v2
	v_mov_b32_e32 v60, v2
	v_mov_b32_e32 v61, v2
	v_mov_b32_e32 v10, v2
	v_mov_b32_e32 v11, v2
	v_mov_b32_e32 v12, v2
	v_mov_b32_e32 v13, v2
	v_mov_b32_e32 v14, v2
	v_mov_b32_e32 v15, v2
	v_mov_b32_e32 v16, v2
	v_mov_b32_e32 v17, v2
	v_mov_b32_e32 v26, v2
	v_mov_b32_e32 v27, v2
	v_mov_b32_e32 v28, v2
	v_mov_b32_e32 v29, v2
	v_mov_b32_e32 v34, v2
	v_mov_b32_e32 v35, v2
	v_mov_b32_e32 v36, v2
	v_mov_b32_e32 v37, v2
	v_mov_b32_e32 v46, v2
	v_mov_b32_e32 v47, v2
	v_mov_b32_e32 v48, v2
	v_mov_b32_e32 v49, v2
	v_mov_b32_e32 v50, v2
	v_mov_b32_e32 v51, v2
	v_mov_b32_e32 v52, v2
	v_mov_b32_e32 v53, v2
	v_mov_b32_e32 v62, v2
	v_mov_b32_e32 v63, v2
	v_mov_b32_e32 v64, v2
	v_mov_b32_e32 v65, v2
	v_mov_b32_e32 v66, v2
	v_mov_b32_e32 v67, v2
	v_mov_b32_e32 v68, v2
	v_mov_b32_e32 v69, v2
	v_mov_b32_e32 v70, v2
	v_mov_b32_e32 v71, v2
	v_mov_b32_e32 v72, v2
	v_mov_b32_e32 v73, v2
	v_mov_b32_e32 v74, v2
	v_mov_b32_e32 v75, v2
	v_mov_b32_e32 v76, v2
	v_mov_b32_e32 v77, v2
	v_mov_b32_e32 v86, v2
	v_mov_b32_e32 v87, v2
	v_mov_b32_e32 v88, v2
	v_mov_b32_e32 v89, v2
	v_mov_b32_e32 v90, v2
	v_mov_b32_e32 v91, v2
	v_mov_b32_e32 v92, v2
	v_mov_b32_e32 v93, v2
	v_mov_b32_e32 v118, v2
	v_mov_b32_e32 v119, v2
	v_mov_b32_e32 v120, v2
	v_mov_b32_e32 v121, v2
	v_mov_b32_e32 v122, v2
	v_mov_b32_e32 v123, v2
	v_mov_b32_e32 v124, v2
	v_mov_b32_e32 v125, v2
	v_mov_b32_e32 v134, v2
	v_mov_b32_e32 v135, v2
	v_mov_b32_e32 v136, v2
	v_mov_b32_e32 v137, v2
	v_mov_b32_e32 v138, v2
	v_mov_b32_e32 v139, v2
	v_mov_b32_e32 v140, v2
	v_mov_b32_e32 v141, v2
	v_mov_b32_e32 v78, v2
	v_mov_b32_e32 v79, v2
	v_mov_b32_e32 v80, v2
	v_mov_b32_e32 v81, v2
	v_mov_b32_e32 v82, v2
	v_mov_b32_e32 v83, v2
	v_mov_b32_e32 v84, v2
	v_mov_b32_e32 v85, v2
	v_mov_b32_e32 v110, v2
	v_mov_b32_e32 v111, v2
	v_mov_b32_e32 v112, v2
	v_mov_b32_e32 v113, v2
	v_mov_b32_e32 v114, v2
	v_mov_b32_e32 v115, v2
	v_mov_b32_e32 v116, v2
	v_mov_b32_e32 v117, v2
	v_mov_b32_e32 v126, v2
	v_mov_b32_e32 v127, v2
	v_mov_b32_e32 v128, v2
	v_mov_b32_e32 v129, v2
	v_mov_b32_e32 v130, v2
	v_mov_b32_e32 v131, v2
	v_mov_b32_e32 v132, v2
	v_mov_b32_e32 v133, v2
	v_mov_b32_e32 v142, v2
	v_mov_b32_e32 v143, v2
	v_mov_b32_e32 v144, v2
	v_mov_b32_e32 v145, v2
	v_mov_b32_e32 v146, v2
	v_mov_b32_e32 v147, v2
	v_mov_b32_e32 v148, v2
	v_mov_b32_e32 v149, v2
	.p2align 6

;     ...
; #pragma unroll
;         for (int a = 0; a < 2; ++a)
; #pragma unroll
;             for (int b = 0; b < 2; ++b)
; #pragma unroll
;                 for (int m = 0; m < 4; ++m)
; #pragma unroll
;                     for (int n = 0; n < 2; ++n) acc[a][b][m][n] = (f32x4){0.f, 0.f, 0.f, 0.f};
;         cur = nxt; cA = nA; cB = nB; nt = cur.nt; ++ui;
.LBB0_1453:
	s_add_u32 s9, s30, 0x100
	v_mov_b32_e32 v2, 0
	s_addc_u32 s23, s31, 0
	s_mov_b32 s25, 2
	v_mov_b32_e32 v3, v2
	v_mov_b32_e32 v4, v2
	v_mov_b32_e32 v5, v2
	v_mov_b32_e32 v6, v2
	v_mov_b32_e32 v7, v2
	v_mov_b32_e32 v8, v2
	v_mov_b32_e32 v9, v2
	v_mov_b32_e32 v18, v2
	v_mov_b32_e32 v19, v2
	v_mov_b32_e32 v20, v2
	v_mov_b32_e32 v21, v2
	v_mov_b32_e32 v22, v2
	v_mov_b32_e32 v23, v2
	v_mov_b32_e32 v24, v2
	v_mov_b32_e32 v25, v2
	v_mov_b32_e32 v40, v2
	v_mov_b32_e32 v41, v2
	v_mov_b32_e32 v42, v2
	v_mov_b32_e32 v43, v2
	v_mov_b32_e32 v44, v2
	v_mov_b32_e32 v45, v2
	v_mov_b32_e32 v46, v2
	v_mov_b32_e32 v47, v2
	v_mov_b32_e32 v56, v2
	v_mov_b32_e32 v57, v2
	v_mov_b32_e32 v58, v2
	v_mov_b32_e32 v59, v2
	v_mov_b32_e32 v60, v2
	v_mov_b32_e32 v61, v2
	v_mov_b32_e32 v62, v2
	v_mov_b32_e32 v63, v2
	v_mov_b32_e32 v10, v2
	v_mov_b32_e32 v11, v2
	v_mov_b32_e32 v12, v2
	v_mov_b32_e32 v13, v2
	v_mov_b32_e32 v14, v2
	v_mov_b32_e32 v15, v2
	v_mov_b32_e32 v16, v2
	v_mov_b32_e32 v17, v2
	v_mov_b32_e32 v26, v2
	v_mov_b32_e32 v27, v2
	v_mov_b32_e32 v28, v2
	v_mov_b32_e32 v29, v2
	v_mov_b32_e32 v36, v2
	v_mov_b32_e32 v37, v2
	v_mov_b32_e32 v38, v2
	v_mov_b32_e32 v39, v2
	v_mov_b32_e32 v48, v2
	v_mov_b32_e32 v49, v2
	v_mov_b32_e32 v50, v2
	v_mov_b32_e32 v51, v2
	v_mov_b32_e32 v52, v2
	v_mov_b32_e32 v53, v2
	v_mov_b32_e32 v54, v2
	v_mov_b32_e32 v55, v2
	v_mov_b32_e32 v64, v2
	v_mov_b32_e32 v65, v2
	v_mov_b32_e32 v66, v2
	v_mov_b32_e32 v67, v2
	v_mov_b32_e32 v68, v2
	v_mov_b32_e32 v69, v2
	v_mov_b32_e32 v70, v2
	v_mov_b32_e32 v71, v2
	v_mov_b32_e32 v92, v2
	v_mov_b32_e32 v93, v2
	v_mov_b32_e32 v94, v2
	v_mov_b32_e32 v95, v2
	v_mov_b32_e32 v96, v2
	v_mov_b32_e32 v97, v2
	v_mov_b32_e32 v98, v2
	v_mov_b32_e32 v99, v2
	v_mov_b32_e32 v108, v2
	v_mov_b32_e32 v109, v2
	v_mov_b32_e32 v110, v2
	v_mov_b32_e32 v111, v2
	v_mov_b32_e32 v112, v2
	v_mov_b32_e32 v113, v2
	v_mov_b32_e32 v114, v2
	v_mov_b32_e32 v115, v2
	v_mov_b32_e32 v124, v2
	v_mov_b32_e32 v125, v2
	v_mov_b32_e32 v126, v2
	v_mov_b32_e32 v127, v2
	v_mov_b32_e32 v128, v2
	v_mov_b32_e32 v129, v2
	v_mov_b32_e32 v130, v2
	v_mov_b32_e32 v131, v2
	v_mov_b32_e32 v140, v2
	v_mov_b32_e32 v141, v2
	v_mov_b32_e32 v142, v2
	v_mov_b32_e32 v143, v2
	v_mov_b32_e32 v144, v2
	v_mov_b32_e32 v145, v2
	v_mov_b32_e32 v146, v2
	v_mov_b32_e32 v147, v2
	v_mov_b32_e32 v100, v2
	v_mov_b32_e32 v101, v2
	v_mov_b32_e32 v102, v2
	v_mov_b32_e32 v103, v2
	v_mov_b32_e32 v104, v2
	v_mov_b32_e32 v105, v2
	v_mov_b32_e32 v106, v2
	v_mov_b32_e32 v107, v2
	v_mov_b32_e32 v116, v2
	v_mov_b32_e32 v117, v2
	v_mov_b32_e32 v118, v2
	v_mov_b32_e32 v119, v2
	v_mov_b32_e32 v120, v2
	v_mov_b32_e32 v121, v2
	v_mov_b32_e32 v122, v2
	v_mov_b32_e32 v123, v2
	v_mov_b32_e32 v132, v2
	v_mov_b32_e32 v133, v2
	v_mov_b32_e32 v134, v2
	v_mov_b32_e32 v135, v2
	v_mov_b32_e32 v136, v2
	v_mov_b32_e32 v137, v2
	v_mov_b32_e32 v138, v2
	v_mov_b32_e32 v139, v2
	v_mov_b32_e32 v148, v2
	v_mov_b32_e32 v149, v2
	v_mov_b32_e32 v150, v2
	v_mov_b32_e32 v151, v2
	v_mov_b32_e32 v84, v2
	v_mov_b32_e32 v85, v2
	v_mov_b32_e32 v86, v2
	v_mov_b32_e32 v87, v2
	.p2align 6
